# GEMM tile starts re-touch the following 32 KiB of code (K loop + epilogue) because L2 turns over within a phase
# baseline (speedup 1.0000x reference)
; #define PG8_STAGE(bufoff, gbase, voff) do { _Pragma("unroll") for (int _i = 0; _i < 2; ++_i) \
;         __builtin_amdgcn_global_load_lds((const unsigned*)((const char*)(gbase) + (voff)[_i]), (PG8_LAS unsigned*)(lds + (bufoff) + ldsw + _i * 8192), 16, 0, 0); } while (0)
; #define PG8_WAIT_V(n) asm volatile("s_waitcnt vmcnt(" #n ")" ::: "memory")
; #define PG8_BAR __builtin_amdgcn_s_barrier()
; template <class Epi>
; DI void gemm_phase(PG8_LAS unsigned char* lds, const Gemm g, const StaticOrder& S, const Epi& E) {
;     ...
;     Unit cur, nxt; int ui = 0;
;     if (!S.next(0, cur)) return;
;     f32x4 acc[2][2][4][2];
; #pragma unroll
;     for (int a = 0; a < 2; ++a)
; #pragma unroll
;         for (int b = 0; b < 2; ++b)
; #pragma unroll
;             for (int m = 0; m < 4; ++m)
; #pragma unroll
;                 for (int n = 0; n < 2; ++n) acc[a][b][m][n] = (f32x4){0.f, 0.f, 0.f, 0.f};
;     bf16x8 At[4][2], B0[2][2], B1[2][2];
;     const char* cA = (const char*)g.A + (size_t)cur.pm * tstepA + (size_t)cur.pn * g.a_pn_off; const char* cB = (const char*)g.Bt + (size_t)cur.pn * tstepB;
;     PG8_STAGE(PG8_SB(0, 0), cB, voffB); PG8_STAGE(PG8_SB(0, 1), cB + hstepB, voffB); PG8_STAGE(PG8_SA(0, 0), cA, voffA); PG8_STAGE(PG8_SA(0, 1), cA + hstepA, voffA);
;     if (wr == 1) PG8_BAR;
;     PG8_WAIT_V(2); PG8_BAR;
;     PG8_STAGE(PG8_SB(1, 0), cB + kstep, voffB); PG8_STAGE(PG8_SA(1, 0), cA + kstep, voffA); PG8_STAGE(PG8_SB(1, 1), cB + hstepB + kstep, voffB);
;     PG8_WAIT_V(6); PG8_BAR;
;     for (;;) {
;         const bool has_next = S.next(ui + 1, nxt);
;         const char* nA = has_next ? (const char*)g.A + (size_t)nxt.pm * tstepA + (size_t)nxt.pn * g.a_pn_off : cA; const char* nB = has_next ? (const char*)g.Bt + (size_t)nxt.pn * tstepB : cB;
;     DI void operator()(const f32x4 (&acc)[2][2][4][2], const pg8::Unit& u, int wr, int wc, int fr, int fq) const {
;     ...
;         const int colb = pn * 256 + wc * 32 + 8 * fq - c0;
;         f32x4 bia[2][2];
; #pragma unroll
;         for (int bj = 0; bj < 2; ++bj) { bia[bj][0] = *(const f32x4*)(bin + boff + colb + bj * 128); bia[bj][1] = *(const f32x4*)(bin + boff + colb + bj * 128 + 4); }
.LBB0_282:
	s_getpc_b64 s[100:101]
	v_lshlrev_b32_e32 v222, 6, v250
	global_load_dword v253, v222, s[100:101]
	v_readlane_b32 s78, v254, 14
	v_readlane_b32 s79, v254, 15
	s_lshl_b32 s74, s27, 8
	s_or_b32 s74, s74, s43
	s_cmp_lt_u32 s27, 8
	s_cselect_b32 s75, 0, 8
	s_add_i32 s74, s74, s75
	v_lshl_add_u32 v244, v171, 3, s74
	v_lshlrev_b32_e32 v244, 2, v244
	s_nop 1
	global_load_dwordx4 v[228:231], v244, s[78:79]
	global_load_dwordx4 v[232:235], v244, s[78:79] offset:16
	global_load_dwordx4 v[236:239], v244, s[78:79] offset:528
	global_load_dwordx4 v[240:243], v244, s[78:79] offset:512
	s_ashr_i32 s17, s16, 31
	s_lshl_b64 s[22:23], s[16:17], 19
	s_add_u32 s22, s94, s22
	s_addc_u32 s23, s95, s23
	s_and_b64 s[24:25], s[0:1], exec
	s_cselect_b32 s6, s23, s29
	s_cselect_b32 s17, s22, s28
	s_ashr_i32 s15, s14, 31
	s_lshl_b64 s[24:25], s[14:15], 19
	s_add_u32 s24, s70, s24
	s_addc_u32 s25, s71, s25
	s_and_b64 s[34:35], s[0:1], exec
	s_cselect_b32 s15, s25, s31
	s_cselect_b32 s50, s24, s30
	s_add_u32 s28, s28, 0x40080
	s_addc_u32 s29, s29, 0
	s_add_u32 s51, s30, 0x100
	v_mov_b32_e32 v0, 0
	s_addc_u32 s52, s31, 0
	s_mov_b32 s53, -2
	v_mov_b32_e32 v1, v0
	v_mov_b32_e32 v2, v0
	v_mov_b32_e32 v3, v0
	v_mov_b32_e32 v4, v0
	v_mov_b32_e32 v5, v0
	v_mov_b32_e32 v6, v0
	v_mov_b32_e32 v7, v0
	v_mov_b32_e32 v16, v0
	v_mov_b32_e32 v17, v0
	v_mov_b32_e32 v18, v0
	v_mov_b32_e32 v19, v0
	v_mov_b32_e32 v20, v0
	v_mov_b32_e32 v21, v0
	v_mov_b32_e32 v22, v0
	v_mov_b32_e32 v23, v0
	v_mov_b32_e32 v32, v0
	v_mov_b32_e32 v33, v0
	v_mov_b32_e32 v34, v0
	v_mov_b32_e32 v35, v0
	v_mov_b32_e32 v36, v0
	v_mov_b32_e32 v37, v0
	v_mov_b32_e32 v38, v0
	v_mov_b32_e32 v39, v0
	v_mov_b32_e32 v48, v0
	v_mov_b32_e32 v49, v0
	v_mov_b32_e32 v50, v0
	v_mov_b32_e32 v51, v0
	v_mov_b32_e32 v52, v0
	v_mov_b32_e32 v53, v0
	v_mov_b32_e32 v54, v0
	v_mov_b32_e32 v55, v0
	v_mov_b32_e32 v8, v0
	v_mov_b32_e32 v9, v0
	v_mov_b32_e32 v10, v0
	v_mov_b32_e32 v11, v0
	v_mov_b32_e32 v12, v0
	v_mov_b32_e32 v13, v0
	v_mov_b32_e32 v14, v0
	v_mov_b32_e32 v15, v0
	v_mov_b32_e32 v24, v0
	v_mov_b32_e32 v25, v0
	v_mov_b32_e32 v26, v0
	v_mov_b32_e32 v27, v0
	v_mov_b32_e32 v28, v0
	v_mov_b32_e32 v29, v0
	v_mov_b32_e32 v30, v0
	v_mov_b32_e32 v31, v0
	v_mov_b32_e32 v40, v0
	v_mov_b32_e32 v41, v0
	v_mov_b32_e32 v42, v0
	v_mov_b32_e32 v43, v0
	v_mov_b32_e32 v44, v0
	v_mov_b32_e32 v45, v0
	v_mov_b32_e32 v46, v0
	v_mov_b32_e32 v47, v0
	v_mov_b32_e32 v56, v0
	v_mov_b32_e32 v57, v0
	v_mov_b32_e32 v58, v0
	v_mov_b32_e32 v59, v0
	v_mov_b32_e32 v60, v0
	v_mov_b32_e32 v61, v0
	v_mov_b32_e32 v62, v0
	v_mov_b32_e32 v63, v0
	v_mov_b32_e32 v64, v0
	v_mov_b32_e32 v65, v0
	v_mov_b32_e32 v66, v0
	v_mov_b32_e32 v67, v0
	v_mov_b32_e32 v68, v0
	v_mov_b32_e32 v69, v0
	v_mov_b32_e32 v70, v0
	v_mov_b32_e32 v71, v0
	v_mov_b32_e32 v80, v0
	v_mov_b32_e32 v81, v0
	v_mov_b32_e32 v82, v0
	v_mov_b32_e32 v83, v0
	v_mov_b32_e32 v84, v0
	v_mov_b32_e32 v85, v0
	v_mov_b32_e32 v86, v0
	v_mov_b32_e32 v87, v0
	v_mov_b32_e32 v104, v0
	v_mov_b32_e32 v105, v0
	v_mov_b32_e32 v106, v0
	v_mov_b32_e32 v107, v0
	v_mov_b32_e32 v108, v0
	v_mov_b32_e32 v109, v0
	v_mov_b32_e32 v110, v0
	v_mov_b32_e32 v111, v0
	v_mov_b32_e32 v128, v0
	v_mov_b32_e32 v129, v0
	v_mov_b32_e32 v130, v0
	v_mov_b32_e32 v131, v0
	v_mov_b32_e32 v132, v0
	v_mov_b32_e32 v133, v0
	v_mov_b32_e32 v134, v0
	v_mov_b32_e32 v135, v0
	v_mov_b32_e32 v72, v0
	v_mov_b32_e32 v73, v0
	v_mov_b32_e32 v74, v0
	v_mov_b32_e32 v75, v0
	v_mov_b32_e32 v76, v0
	v_mov_b32_e32 v77, v0
	v_mov_b32_e32 v78, v0
	v_mov_b32_e32 v79, v0
	v_mov_b32_e32 v88, v0
	v_mov_b32_e32 v89, v0
	v_mov_b32_e32 v90, v0
	v_mov_b32_e32 v91, v0
	v_mov_b32_e32 v100, v0
	v_mov_b32_e32 v101, v0
	v_mov_b32_e32 v102, v0
	v_mov_b32_e32 v103, v0
	v_mov_b32_e32 v120, v0
	v_mov_b32_e32 v121, v0
	v_mov_b32_e32 v122, v0
	v_mov_b32_e32 v123, v0
	v_mov_b32_e32 v124, v0
	v_mov_b32_e32 v125, v0
	v_mov_b32_e32 v126, v0
	v_mov_b32_e32 v127, v0
	v_mov_b32_e32 v136, v0
	v_mov_b32_e32 v137, v0
	v_mov_b32_e32 v138, v0
	v_mov_b32_e32 v139, v0
	v_mov_b32_e32 v140, v0
	v_mov_b32_e32 v141, v0
	v_mov_b32_e32 v142, v0
	v_mov_b32_e32 v143, v0

; #define PG8_STAGE(bufoff, gbase, voff) do { _Pragma("unroll") for (int _i = 0; _i < 2; ++_i) \
;         __builtin_amdgcn_global_load_lds((const unsigned*)((const char*)(gbase) + (voff)[_i]), (PG8_LAS unsigned*)(lds + (bufoff) + ldsw + _i * 8192), 16, 0, 0); } while (0)
; #define PG8_WAIT_V(n) asm volatile("s_waitcnt vmcnt(" #n ")" ::: "memory")
; #define PG8_BAR __builtin_amdgcn_s_barrier()
; template <class Epi>
; DI void gemm_phase(PG8_LAS unsigned char* lds, const Gemm g, const StaticOrder& S, const Epi& E) {
;     ...
;     Unit cur, nxt; int ui = 0;
;     if (!S.next(0, cur)) return;
;     f32x4 acc[2][2][4][2];
; #pragma unroll
;     for (int a = 0; a < 2; ++a)
; #pragma unroll
;         for (int b = 0; b < 2; ++b)
; #pragma unroll
;             for (int m = 0; m < 4; ++m)
; #pragma unroll
;                 for (int n = 0; n < 2; ++n) acc[a][b][m][n] = (f32x4){0.f, 0.f, 0.f, 0.f};
;     bf16x8 At[4][2], B0[2][2], B1[2][2];
;     const char* cA = (const char*)g.A + (size_t)cur.pm * tstepA + (size_t)cur.pn * g.a_pn_off; const char* cB = (const char*)g.Bt + (size_t)cur.pn * tstepB;
;     PG8_STAGE(PG8_SB(0, 0), cB, voffB); PG8_STAGE(PG8_SB(0, 1), cB + hstepB, voffB); PG8_STAGE(PG8_SA(0, 0), cA, voffA); PG8_STAGE(PG8_SA(0, 1), cA + hstepA, voffA);
;     if (wr == 1) PG8_BAR;
;     PG8_WAIT_V(2); PG8_BAR;
;     PG8_STAGE(PG8_SB(1, 0), cB + kstep, voffB); PG8_STAGE(PG8_SA(1, 0), cA + kstep, voffA); PG8_STAGE(PG8_SB(1, 1), cB + hstepB + kstep, voffB);
;     PG8_WAIT_V(6); PG8_BAR;
;     for (;;) {
;         const bool has_next = S.next(ui + 1, nxt);
;         const char* nA = has_next ? (const char*)g.A + (size_t)nxt.pm * tstepA + (size_t)nxt.pn * g.a_pn_off : cA; const char* nB = has_next ? (const char*)g.Bt + (size_t)nxt.pn * tstepB : cB;
.LBB0_654:
	s_getpc_b64 s[100:101]
	v_lshlrev_b32_e32 v222, 6, v250
	global_load_dword v253, v222, s[100:101]
	s_ashr_i32 s13, s12, 31
	s_lshl_b64 s[14:15], s[12:13], 18
	s_add_u32 s14, s68, s14
	s_addc_u32 s15, s69, s15
	s_and_b64 s[16:17], s[0:1], exec
	s_cselect_b32 s13, s15, s25
	s_cselect_b32 s47, s14, s24
	s_ashr_i32 s11, s10, 31
	s_lshl_b64 s[16:17], s[10:11], 18
	s_add_u32 s16, s30, s16
	s_addc_u32 s17, s31, s17
	s_and_b64 s[28:29], s[0:1], exec
	s_cselect_b32 s11, s17, s27
	s_cselect_b32 s48, s16, s26
	s_add_u32 s24, s24, 0x20080
	s_addc_u32 s25, s25, 0
	s_add_u32 s49, s26, 0x100
	v_mov_b32_e32 v4, 0
	s_addc_u32 s50, s27, 0
	s_mov_b32 s51, -2
	v_mov_b32_e32 v5, v4
	v_mov_b32_e32 v6, v4
	v_mov_b32_e32 v7, v4
	v_mov_b32_e32 v0, v4
	v_mov_b32_e32 v1, v4
	v_mov_b32_e32 v2, v4
	v_mov_b32_e32 v3, v4
	v_mov_b32_e32 v20, v4
	v_mov_b32_e32 v21, v4
	v_mov_b32_e32 v22, v4
	v_mov_b32_e32 v23, v4
	v_mov_b32_e32 v16, v4
	v_mov_b32_e32 v17, v4
	v_mov_b32_e32 v18, v4
	v_mov_b32_e32 v19, v4
	v_mov_b32_e32 v36, v4
	v_mov_b32_e32 v37, v4
	v_mov_b32_e32 v38, v4
	v_mov_b32_e32 v39, v4
	v_mov_b32_e32 v32, v4
	v_mov_b32_e32 v33, v4
	v_mov_b32_e32 v34, v4
	v_mov_b32_e32 v35, v4
	v_mov_b32_e32 v52, v4
	v_mov_b32_e32 v53, v4
	v_mov_b32_e32 v54, v4
	v_mov_b32_e32 v55, v4
	v_mov_b32_e32 v48, v4
	v_mov_b32_e32 v49, v4
	v_mov_b32_e32 v50, v4
	v_mov_b32_e32 v51, v4
	v_mov_b32_e32 v12, v4
	v_mov_b32_e32 v13, v4
	v_mov_b32_e32 v14, v4
	v_mov_b32_e32 v15, v4
	v_mov_b32_e32 v8, v4
	v_mov_b32_e32 v9, v4
	v_mov_b32_e32 v10, v4
	v_mov_b32_e32 v11, v4
	v_mov_b32_e32 v28, v4
	v_mov_b32_e32 v29, v4
	v_mov_b32_e32 v30, v4
	v_mov_b32_e32 v31, v4
	v_mov_b32_e32 v24, v4
	v_mov_b32_e32 v25, v4
	v_mov_b32_e32 v26, v4
	v_mov_b32_e32 v27, v4
	v_mov_b32_e32 v44, v4
	v_mov_b32_e32 v45, v4
	v_mov_b32_e32 v46, v4
	v_mov_b32_e32 v47, v4
	v_mov_b32_e32 v40, v4
	v_mov_b32_e32 v41, v4
	v_mov_b32_e32 v42, v4
	v_mov_b32_e32 v43, v4
	v_mov_b32_e32 v60, v4
	v_mov_b32_e32 v61, v4
	v_mov_b32_e32 v62, v4
	v_mov_b32_e32 v63, v4
	v_mov_b32_e32 v56, v4
	v_mov_b32_e32 v57, v4
	v_mov_b32_e32 v58, v4
	v_mov_b32_e32 v59, v4
	v_mov_b32_e32 v68, v4
	v_mov_b32_e32 v69, v4
	v_mov_b32_e32 v70, v4
	v_mov_b32_e32 v71, v4
	v_mov_b32_e32 v64, v4
	v_mov_b32_e32 v65, v4
	v_mov_b32_e32 v66, v4
	v_mov_b32_e32 v67, v4
	v_mov_b32_e32 v84, v4
	v_mov_b32_e32 v85, v4
	v_mov_b32_e32 v86, v4
	v_mov_b32_e32 v87, v4
	v_mov_b32_e32 v80, v4
	v_mov_b32_e32 v81, v4
	v_mov_b32_e32 v82, v4
	v_mov_b32_e32 v83, v4
	v_mov_b32_e32 v100, v4
	v_mov_b32_e32 v101, v4
	v_mov_b32_e32 v102, v4
	v_mov_b32_e32 v103, v4
	v_mov_b32_e32 v96, v4
	v_mov_b32_e32 v97, v4
	v_mov_b32_e32 v98, v4
	v_mov_b32_e32 v99, v4
	v_mov_b32_e32 v116, v4
	v_mov_b32_e32 v117, v4
	v_mov_b32_e32 v118, v4
	v_mov_b32_e32 v119, v4
	v_mov_b32_e32 v112, v4
	v_mov_b32_e32 v113, v4
	v_mov_b32_e32 v114, v4
	v_mov_b32_e32 v115, v4
	v_mov_b32_e32 v76, v4
	v_mov_b32_e32 v77, v4
	v_mov_b32_e32 v78, v4
	v_mov_b32_e32 v79, v4
	v_mov_b32_e32 v72, v4
	v_mov_b32_e32 v73, v4
	v_mov_b32_e32 v74, v4
	v_mov_b32_e32 v75, v4
	v_mov_b32_e32 v92, v4
	v_mov_b32_e32 v93, v4
	v_mov_b32_e32 v94, v4
	v_mov_b32_e32 v95, v4
	v_mov_b32_e32 v88, v4
	v_mov_b32_e32 v89, v4
	v_mov_b32_e32 v90, v4
	v_mov_b32_e32 v91, v4
	v_mov_b32_e32 v108, v4
	v_mov_b32_e32 v109, v4
	v_mov_b32_e32 v110, v4
	v_mov_b32_e32 v111, v4
	v_mov_b32_e32 v104, v4
	v_mov_b32_e32 v105, v4
	v_mov_b32_e32 v106, v4
	v_mov_b32_e32 v107, v4
	v_mov_b32_e32 v124, v4
	v_mov_b32_e32 v125, v4
	v_mov_b32_e32 v126, v4
	v_mov_b32_e32 v127, v4
	v_mov_b32_e32 v120, v4
	v_mov_b32_e32 v121, v4
	v_mov_b32_e32 v122, v4
	v_mov_b32_e32 v123, v4

; #define PG8_STAGE(bufoff, gbase, voff) do { _Pragma("unroll") for (int _i = 0; _i < 2; ++_i) \
;         __builtin_amdgcn_global_load_lds((const unsigned*)((const char*)(gbase) + (voff)[_i]), (PG8_LAS unsigned*)(lds + (bufoff) + ldsw + _i * 8192), 16, 0, 0); } while (0)
; #define PG8_WAIT_V(n) asm volatile("s_waitcnt vmcnt(" #n ")" ::: "memory")
; #define PG8_BAR __builtin_amdgcn_s_barrier()
; template <class Epi>
; DI void gemm_phase(PG8_LAS unsigned char* lds, const Gemm g, const StaticOrder& S, const Epi& E) {
;     ...
;     Unit cur, nxt; int ui = 0;
;     if (!S.next(0, cur)) return;
;     f32x4 acc[2][2][4][2];
; #pragma unroll
;     for (int a = 0; a < 2; ++a)
; #pragma unroll
;         for (int b = 0; b < 2; ++b)
; #pragma unroll
;             for (int m = 0; m < 4; ++m)
; #pragma unroll
;                 for (int n = 0; n < 2; ++n) acc[a][b][m][n] = (f32x4){0.f, 0.f, 0.f, 0.f};
;     bf16x8 At[4][2], B0[2][2], B1[2][2];
;     const char* cA = (const char*)g.A + (size_t)cur.pm * tstepA + (size_t)cur.pn * g.a_pn_off; const char* cB = (const char*)g.Bt + (size_t)cur.pn * tstepB;
;     PG8_STAGE(PG8_SB(0, 0), cB, voffB); PG8_STAGE(PG8_SB(0, 1), cB + hstepB, voffB); PG8_STAGE(PG8_SA(0, 0), cA, voffA); PG8_STAGE(PG8_SA(0, 1), cA + hstepA, voffA);
;     if (wr == 1) PG8_BAR;
;     PG8_WAIT_V(2); PG8_BAR;
;     PG8_STAGE(PG8_SB(1, 0), cB + kstep, voffB); PG8_STAGE(PG8_SA(1, 0), cA + kstep, voffA); PG8_STAGE(PG8_SB(1, 1), cB + hstepB + kstep, voffB);
;     PG8_WAIT_V(6); PG8_BAR;
;     for (;;) {
;         const bool has_next = S.next(ui + 1, nxt);
;         const char* nA = has_next ? (const char*)g.A + (size_t)nxt.pm * tstepA + (size_t)nxt.pn * g.a_pn_off : cA; const char* nB = has_next ? (const char*)g.Bt + (size_t)nxt.pn * tstepB : cB;
.LBB0_851:
	s_getpc_b64 s[100:101]
	v_lshlrev_b32_e32 v222, 6, v250
	global_load_dword v253, v222, s[100:101]
	s_ashr_i32 s21, s20, 31
	s_lshl_b64 s[22:23], s[20:21], 19
	s_add_u32 s22, s68, s22
	s_addc_u32 s23, s69, s23
	s_and_b64 s[24:25], s[4:5], exec
	s_cselect_b32 s21, s23, s29
	s_cselect_b32 s85, s22, s28
	s_ashr_i32 s19, s18, 31
	s_lshl_b64 s[24:25], s[18:19], 19
	s_add_u32 s24, s36, s24
	s_addc_u32 s25, s37, s25
	s_and_b64 s[34:35], s[4:5], exec
	s_cselect_b32 s19, s25, s31
	s_cselect_b32 s86, s24, s30
	s_add_u32 s28, s28, 0x40080
	s_addc_u32 s29, s29, 0
	s_add_u32 s87, s30, 0x100
	v_mov_b32_e32 v0, 0
	s_addc_u32 s90, s31, 0
	s_mov_b32 s91, -2
	v_mov_b32_e32 v1, v0
	v_mov_b32_e32 v2, v0
	v_mov_b32_e32 v3, v0
	v_mov_b32_e32 v4, v0
	v_mov_b32_e32 v5, v0
	v_mov_b32_e32 v6, v0
	v_mov_b32_e32 v7, v0
	v_mov_b32_e32 v16, v0
	v_mov_b32_e32 v17, v0
	v_mov_b32_e32 v18, v0
	v_mov_b32_e32 v19, v0
	v_mov_b32_e32 v20, v0
	v_mov_b32_e32 v21, v0
	v_mov_b32_e32 v22, v0
	v_mov_b32_e32 v23, v0
	v_mov_b32_e32 v32, v0
	v_mov_b32_e32 v33, v0
	v_mov_b32_e32 v34, v0
	v_mov_b32_e32 v35, v0
	v_mov_b32_e32 v36, v0
	v_mov_b32_e32 v37, v0
	v_mov_b32_e32 v38, v0
	v_mov_b32_e32 v39, v0
	v_mov_b32_e32 v48, v0
	v_mov_b32_e32 v49, v0
	v_mov_b32_e32 v50, v0
	v_mov_b32_e32 v51, v0
	v_mov_b32_e32 v52, v0
	v_mov_b32_e32 v53, v0
	v_mov_b32_e32 v54, v0
	v_mov_b32_e32 v55, v0
	v_mov_b32_e32 v8, v0
	v_mov_b32_e32 v9, v0
	v_mov_b32_e32 v10, v0
	v_mov_b32_e32 v11, v0
	v_mov_b32_e32 v12, v0
	v_mov_b32_e32 v13, v0
	v_mov_b32_e32 v14, v0
	v_mov_b32_e32 v15, v0
	v_mov_b32_e32 v24, v0
	v_mov_b32_e32 v25, v0
	v_mov_b32_e32 v26, v0
	v_mov_b32_e32 v27, v0
	v_mov_b32_e32 v28, v0
	v_mov_b32_e32 v29, v0
	v_mov_b32_e32 v30, v0
	v_mov_b32_e32 v31, v0
	v_mov_b32_e32 v40, v0
	v_mov_b32_e32 v41, v0
	v_mov_b32_e32 v42, v0
	v_mov_b32_e32 v43, v0
	v_mov_b32_e32 v44, v0
	v_mov_b32_e32 v45, v0
	v_mov_b32_e32 v46, v0
	v_mov_b32_e32 v47, v0
	v_mov_b32_e32 v56, v0
	v_mov_b32_e32 v57, v0
	v_mov_b32_e32 v58, v0
	v_mov_b32_e32 v59, v0
	v_mov_b32_e32 v60, v0
	v_mov_b32_e32 v61, v0
	v_mov_b32_e32 v62, v0
	v_mov_b32_e32 v63, v0
	v_mov_b32_e32 v64, v0
	v_mov_b32_e32 v65, v0
	v_mov_b32_e32 v66, v0
	v_mov_b32_e32 v67, v0
	v_mov_b32_e32 v68, v0
	v_mov_b32_e32 v69, v0
	v_mov_b32_e32 v70, v0
	v_mov_b32_e32 v71, v0
	v_mov_b32_e32 v80, v0
	v_mov_b32_e32 v81, v0
	v_mov_b32_e32 v82, v0
	v_mov_b32_e32 v83, v0
	v_mov_b32_e32 v84, v0
	v_mov_b32_e32 v85, v0
	v_mov_b32_e32 v86, v0
	v_mov_b32_e32 v87, v0
	v_mov_b32_e32 v96, v0
	v_mov_b32_e32 v97, v0
	v_mov_b32_e32 v98, v0
	v_mov_b32_e32 v99, v0
	v_mov_b32_e32 v100, v0
	v_mov_b32_e32 v101, v0
	v_mov_b32_e32 v102, v0
	v_mov_b32_e32 v103, v0
	v_mov_b32_e32 v112, v0
	v_mov_b32_e32 v113, v0
	v_mov_b32_e32 v114, v0
	v_mov_b32_e32 v115, v0
	v_mov_b32_e32 v116, v0
	v_mov_b32_e32 v117, v0
	v_mov_b32_e32 v118, v0
	v_mov_b32_e32 v119, v0
	v_mov_b32_e32 v72, v0
	v_mov_b32_e32 v73, v0
	v_mov_b32_e32 v74, v0
	v_mov_b32_e32 v75, v0
	v_mov_b32_e32 v76, v0
	v_mov_b32_e32 v77, v0
	v_mov_b32_e32 v78, v0
	v_mov_b32_e32 v79, v0
	v_mov_b32_e32 v88, v0
	v_mov_b32_e32 v89, v0
	v_mov_b32_e32 v90, v0
	v_mov_b32_e32 v91, v0
	v_mov_b32_e32 v92, v0
	v_mov_b32_e32 v93, v0
	v_mov_b32_e32 v94, v0
	v_mov_b32_e32 v95, v0
	v_mov_b32_e32 v104, v0
	v_mov_b32_e32 v105, v0
	v_mov_b32_e32 v106, v0
	v_mov_b32_e32 v107, v0
	v_mov_b32_e32 v108, v0
	v_mov_b32_e32 v109, v0
	v_mov_b32_e32 v110, v0
	v_mov_b32_e32 v111, v0
	v_mov_b32_e32 v120, v0
	v_mov_b32_e32 v121, v0
	v_mov_b32_e32 v122, v0
	v_mov_b32_e32 v123, v0
	v_mov_b32_e32 v124, v0
	v_mov_b32_e32 v125, v0
	v_mov_b32_e32 v126, v0
	v_mov_b32_e32 v127, v0

; #define PG8_STAGE(bufoff, gbase, voff) do { _Pragma("unroll") for (int _i = 0; _i < 2; ++_i) \
;         __builtin_amdgcn_global_load_lds((const unsigned*)((const char*)(gbase) + (voff)[_i]), (PG8_LAS unsigned*)(lds + (bufoff) + ldsw + _i * 8192), 16, 0, 0); } while (0)
; #define PG8_WAIT_V(n) asm volatile("s_waitcnt vmcnt(" #n ")" ::: "memory")
; #define PG8_BAR __builtin_amdgcn_s_barrier()
; template <class Epi>
; DI void gemm_phase(PG8_LAS unsigned char* lds, const Gemm g, const StaticOrder& S, const Epi& E) {
;     ...
;     Unit cur, nxt; int ui = 0;
;     if (!S.next(0, cur)) return;
;     f32x4 acc[2][2][4][2];
; #pragma unroll
;     for (int a = 0; a < 2; ++a)
; #pragma unroll
;         for (int b = 0; b < 2; ++b)
; #pragma unroll
;             for (int m = 0; m < 4; ++m)
; #pragma unroll
;                 for (int n = 0; n < 2; ++n) acc[a][b][m][n] = (f32x4){0.f, 0.f, 0.f, 0.f};
;     bf16x8 At[4][2], B0[2][2], B1[2][2];
;     const char* cA = (const char*)g.A + (size_t)cur.pm * tstepA + (size_t)cur.pn * g.a_pn_off; const char* cB = (const char*)g.Bt + (size_t)cur.pn * tstepB;
;     PG8_STAGE(PG8_SB(0, 0), cB, voffB); PG8_STAGE(PG8_SB(0, 1), cB + hstepB, voffB); PG8_STAGE(PG8_SA(0, 0), cA, voffA); PG8_STAGE(PG8_SA(0, 1), cA + hstepA, voffA);
;     if (wr == 1) PG8_BAR;
;     PG8_WAIT_V(2); PG8_BAR;
;     PG8_STAGE(PG8_SB(1, 0), cB + kstep, voffB); PG8_STAGE(PG8_SA(1, 0), cA + kstep, voffA); PG8_STAGE(PG8_SB(1, 1), cB + hstepB + kstep, voffB);
;     PG8_WAIT_V(6); PG8_BAR;
;     for (;;) {
;         const bool has_next = S.next(ui + 1, nxt);
;         const char* nA = has_next ? (const char*)g.A + (size_t)nxt.pm * tstepA + (size_t)nxt.pn * g.a_pn_off : cA; const char* nB = has_next ? (const char*)g.Bt + (size_t)nxt.pn * tstepB : cB;
.LBB0_927:
	s_getpc_b64 s[100:101]
	v_lshlrev_b32_e32 v222, 6, v250
	v_min_u32_e32 v222, 0x7c00, v222
	global_load_dword v253, v222, s[100:101]
	s_ashr_i32 s29, s28, 31
	s_lshl_b64 s[30:31], s[28:29], 19
	s_add_u32 s30, s96, s30
	s_addc_u32 s31, s97, s31
	s_and_b64 s[34:35], s[4:5], exec
	s_cselect_b32 s29, s31, s39
	s_cselect_b32 s85, s30, s38
	s_ashr_i32 s27, s26, 31
	s_lshl_b64 s[34:35], s[26:27], 19
	s_add_u32 s34, s15, s34
	s_addc_u32 s35, s44, s35
	s_and_b64 s[42:43], s[4:5], exec
	s_cselect_b32 s27, s35, s41
	s_cselect_b32 s86, s34, s40
	s_add_u32 s38, s38, 0x40080
	s_addc_u32 s39, s39, 0
	s_add_u32 s87, s40, 0x100
	v_mov_b32_e32 v0, 0
	s_addc_u32 s90, s41, 0
	s_mov_b32 s91, -2
	v_mov_b32_e32 v1, v0
	v_mov_b32_e32 v2, v0
	v_mov_b32_e32 v3, v0
	v_mov_b32_e32 v4, v0
	v_mov_b32_e32 v5, v0
	v_mov_b32_e32 v6, v0
	v_mov_b32_e32 v7, v0
	v_mov_b32_e32 v16, v0
	v_mov_b32_e32 v17, v0
	v_mov_b32_e32 v18, v0
	v_mov_b32_e32 v19, v0
	v_mov_b32_e32 v20, v0
	v_mov_b32_e32 v21, v0
	v_mov_b32_e32 v22, v0
	v_mov_b32_e32 v23, v0
	v_mov_b32_e32 v32, v0
	v_mov_b32_e32 v33, v0
	v_mov_b32_e32 v34, v0
	v_mov_b32_e32 v35, v0
	v_mov_b32_e32 v36, v0
	v_mov_b32_e32 v37, v0
	v_mov_b32_e32 v38, v0
	v_mov_b32_e32 v39, v0
	v_mov_b32_e32 v48, v0
	v_mov_b32_e32 v49, v0
	v_mov_b32_e32 v50, v0
	v_mov_b32_e32 v51, v0
	v_mov_b32_e32 v52, v0
	v_mov_b32_e32 v53, v0
	v_mov_b32_e32 v54, v0
	v_mov_b32_e32 v55, v0
	v_mov_b32_e32 v8, v0
	v_mov_b32_e32 v9, v0
	v_mov_b32_e32 v10, v0
	v_mov_b32_e32 v11, v0
	v_mov_b32_e32 v12, v0
	v_mov_b32_e32 v13, v0
	v_mov_b32_e32 v14, v0
	v_mov_b32_e32 v15, v0
	v_mov_b32_e32 v24, v0
	v_mov_b32_e32 v25, v0
	v_mov_b32_e32 v26, v0
	v_mov_b32_e32 v27, v0
	v_mov_b32_e32 v28, v0
	v_mov_b32_e32 v29, v0
	v_mov_b32_e32 v30, v0
	v_mov_b32_e32 v31, v0
	v_mov_b32_e32 v40, v0
	v_mov_b32_e32 v41, v0
	v_mov_b32_e32 v42, v0
	v_mov_b32_e32 v43, v0
	v_mov_b32_e32 v44, v0
	v_mov_b32_e32 v45, v0
	v_mov_b32_e32 v46, v0
	v_mov_b32_e32 v47, v0
	v_mov_b32_e32 v56, v0
	v_mov_b32_e32 v57, v0
	v_mov_b32_e32 v58, v0
	v_mov_b32_e32 v59, v0
	v_mov_b32_e32 v60, v0
	v_mov_b32_e32 v61, v0
	v_mov_b32_e32 v62, v0
	v_mov_b32_e32 v63, v0
	v_mov_b32_e32 v64, v0
	v_mov_b32_e32 v65, v0
	v_mov_b32_e32 v66, v0
	v_mov_b32_e32 v67, v0
	v_mov_b32_e32 v68, v0
	v_mov_b32_e32 v69, v0
	v_mov_b32_e32 v70, v0
	v_mov_b32_e32 v71, v0
	v_mov_b32_e32 v80, v0
	v_mov_b32_e32 v81, v0
	v_mov_b32_e32 v82, v0
	v_mov_b32_e32 v83, v0
	v_mov_b32_e32 v84, v0
	v_mov_b32_e32 v85, v0
	v_mov_b32_e32 v86, v0
	v_mov_b32_e32 v87, v0
	v_mov_b32_e32 v96, v0
	v_mov_b32_e32 v97, v0
	v_mov_b32_e32 v98, v0
	v_mov_b32_e32 v99, v0
	v_mov_b32_e32 v100, v0
	v_mov_b32_e32 v101, v0
	v_mov_b32_e32 v102, v0
	v_mov_b32_e32 v103, v0
	v_mov_b32_e32 v112, v0
	v_mov_b32_e32 v113, v0
	v_mov_b32_e32 v114, v0
	v_mov_b32_e32 v115, v0
	v_mov_b32_e32 v116, v0
	v_mov_b32_e32 v117, v0
	v_mov_b32_e32 v118, v0
	v_mov_b32_e32 v119, v0
	v_mov_b32_e32 v72, v0
	v_mov_b32_e32 v73, v0
	v_mov_b32_e32 v74, v0
	v_mov_b32_e32 v75, v0
	v_mov_b32_e32 v76, v0
	v_mov_b32_e32 v77, v0
	v_mov_b32_e32 v78, v0
	v_mov_b32_e32 v79, v0
	v_mov_b32_e32 v88, v0
	v_mov_b32_e32 v89, v0
	v_mov_b32_e32 v90, v0
	v_mov_b32_e32 v91, v0
	v_mov_b32_e32 v92, v0
	v_mov_b32_e32 v93, v0
	v_mov_b32_e32 v94, v0
	v_mov_b32_e32 v95, v0
	v_mov_b32_e32 v104, v0
	v_mov_b32_e32 v105, v0
	v_mov_b32_e32 v106, v0
	v_mov_b32_e32 v107, v0
	v_mov_b32_e32 v108, v0
	v_mov_b32_e32 v109, v0
	v_mov_b32_e32 v110, v0
	v_mov_b32_e32 v111, v0
	v_mov_b32_e32 v120, v0
	v_mov_b32_e32 v121, v0
	v_mov_b32_e32 v122, v0
	v_mov_b32_e32 v123, v0
	v_mov_b32_e32 v124, v0
	v_mov_b32_e32 v125, v0
	v_mov_b32_e32 v126, v0
	v_mov_b32_e32 v127, v0

; #define PG8_STAGE(bufoff, gbase, voff) do { _Pragma("unroll") for (int _i = 0; _i < 2; ++_i) \
;         __builtin_amdgcn_global_load_lds((const unsigned*)((const char*)(gbase) + (voff)[_i]), (PG8_LAS unsigned*)(lds + (bufoff) + ldsw + _i * 8192), 16, 0, 0); } while (0)
; #define PG8_WAIT_V(n) asm volatile("s_waitcnt vmcnt(" #n ")" ::: "memory")
; #define PG8_BAR __builtin_amdgcn_s_barrier()
; template <class Epi>
; DI void gemm_phase(PG8_LAS unsigned char* lds, const Gemm g, const StaticOrder& S, const Epi& E) {
;     ...
;     Unit cur, nxt; int ui = 0;
;     if (!S.next(0, cur)) return;
;     f32x4 acc[2][2][4][2];
; #pragma unroll
;     for (int a = 0; a < 2; ++a)
; #pragma unroll
;         for (int b = 0; b < 2; ++b)
; #pragma unroll
;             for (int m = 0; m < 4; ++m)
; #pragma unroll
;                 for (int n = 0; n < 2; ++n) acc[a][b][m][n] = (f32x4){0.f, 0.f, 0.f, 0.f};
;     bf16x8 At[4][2], B0[2][2], B1[2][2];
;     const char* cA = (const char*)g.A + (size_t)cur.pm * tstepA + (size_t)cur.pn * g.a_pn_off; const char* cB = (const char*)g.Bt + (size_t)cur.pn * tstepB;
;     PG8_STAGE(PG8_SB(0, 0), cB, voffB); PG8_STAGE(PG8_SB(0, 1), cB + hstepB, voffB); PG8_STAGE(PG8_SA(0, 0), cA, voffA); PG8_STAGE(PG8_SA(0, 1), cA + hstepA, voffA);
;     if (wr == 1) PG8_BAR;
;     PG8_WAIT_V(2); PG8_BAR;
;     PG8_STAGE(PG8_SB(1, 0), cB + kstep, voffB); PG8_STAGE(PG8_SA(1, 0), cA + kstep, voffA); PG8_STAGE(PG8_SB(1, 1), cB + hstepB + kstep, voffB);
;     PG8_WAIT_V(6); PG8_BAR;
;     for (;;) {
;         const bool has_next = S.next(ui + 1, nxt);
;         const char* nA = has_next ? (const char*)g.A + (size_t)nxt.pm * tstepA + (size_t)nxt.pn * g.a_pn_off : cA; const char* nB = has_next ? (const char*)g.Bt + (size_t)nxt.pn * tstepB : cB;
;     DI void operator()(const f32x4 (&acc)[2][2][4][2], const pg8::Unit& u, int wr, int wc, int fr, int fq) const {
;     ...
;         float4 w0v[2], w1v[2], w2v[2], bbv[2];
; #pragma unroll
;         for (int bj = 0; bj < 2; ++bj) {
;             const int hc = (u.pn * 256 + bj * 128 + wc * 32 + 8 * fq) >> 1;
;             w0v[bj] = *(const float4*)(cw + hc); w1v[bj] = *(const float4*)(cw + FH + hc); w2v[bj] = *(const float4*)(cw + 2 * FH + hc); bbv[bj] = *(const float4*)(cb + hc);
.LBB0_1060:
	s_getpc_b64 s[100:101]
	v_lshlrev_b32_e32 v222, 6, v250
	v_min_u32_e32 v222, 0x4b40, v222
	global_load_dword v235, v222, s[100:101]
	s_lshl_b32 s84, s6, 8
	s_or_b32 s84, s84, s49
	v_lshl_add_u32 v251, v197, 3, s84
	v_ashrrev_i32_e32 v251, 1, v251
	v_lshlrev_b32_e32 v251, 2, v251
	global_load_dwordx4 v[236:239], v251, s[58:59]
	global_load_dwordx4 v[240:243], v251, s[22:23]
	global_load_dwordx4 v[244:247], v251, s[24:25]
	global_load_dwordx2 v[248:249], v251, s[60:61]
	global_load_dwordx2 v[252:253], v251, s[60:61] offset:8
	s_ashr_i32 s29, s28, 31
	s_lshl_b64 s[30:31], s[28:29], 19
	s_add_u32 s30, s96, s30
	s_addc_u32 s31, s97, s31
	s_and_b64 s[34:35], s[8:9], exec
	s_cselect_b32 s5, s31, s37
	s_cselect_b32 s7, s30, s36
	s_ashr_i32 s27, s26, 31
	s_lshl_b64 s[34:35], s[26:27], 19
	s_add_u32 s34, s3, s34
	s_addc_u32 s35, s42, s35
	s_and_b64 s[40:41], s[8:9], exec
	s_cselect_b32 s27, s35, s39
	s_cselect_b32 s29, s34, s38
	s_add_u32 s36, s36, 0x40080
	s_addc_u32 s37, s37, 0
	s_add_u32 s78, s38, 0x100
	v_mov_b32_e32 v0, 0
	s_addc_u32 s79, s39, 0
	s_mov_b32 s80, -2
	v_mov_b32_e32 v1, v0
	v_mov_b32_e32 v2, v0
	v_mov_b32_e32 v3, v0
	v_mov_b32_e32 v4, v0
	v_mov_b32_e32 v5, v0
	v_mov_b32_e32 v6, v0
	v_mov_b32_e32 v7, v0
	v_mov_b32_e32 v8, v0
	v_mov_b32_e32 v9, v0
	v_mov_b32_e32 v10, v0
	v_mov_b32_e32 v11, v0
	v_mov_b32_e32 v12, v0
	v_mov_b32_e32 v13, v0
	v_mov_b32_e32 v14, v0
	v_mov_b32_e32 v15, v0
	v_mov_b32_e32 v16, v0
	v_mov_b32_e32 v17, v0
	v_mov_b32_e32 v18, v0
	v_mov_b32_e32 v19, v0
	v_mov_b32_e32 v20, v0
	v_mov_b32_e32 v21, v0
	v_mov_b32_e32 v22, v0
	v_mov_b32_e32 v23, v0
	v_mov_b32_e32 v24, v0
	v_mov_b32_e32 v25, v0
	v_mov_b32_e32 v26, v0
	v_mov_b32_e32 v27, v0
	v_mov_b32_e32 v28, v0
	v_mov_b32_e32 v29, v0
	v_mov_b32_e32 v30, v0
	v_mov_b32_e32 v31, v0
	v_mov_b32_e32 v80, v0
	v_mov_b32_e32 v81, v0
	v_mov_b32_e32 v82, v0
	v_mov_b32_e32 v83, v0
	v_mov_b32_e32 v84, v0
	v_mov_b32_e32 v85, v0
	v_mov_b32_e32 v86, v0
	v_mov_b32_e32 v87, v0
	v_mov_b32_e32 v88, v0
	v_mov_b32_e32 v89, v0
	v_mov_b32_e32 v90, v0
	v_mov_b32_e32 v91, v0
	v_mov_b32_e32 v92, v0
	v_mov_b32_e32 v93, v0
	v_mov_b32_e32 v94, v0
	v_mov_b32_e32 v95, v0
	v_mov_b32_e32 v96, v0
	v_mov_b32_e32 v97, v0
	v_mov_b32_e32 v98, v0
	v_mov_b32_e32 v99, v0
	v_mov_b32_e32 v100, v0
	v_mov_b32_e32 v101, v0
	v_mov_b32_e32 v102, v0
	v_mov_b32_e32 v103, v0
	v_mov_b32_e32 v104, v0
	v_mov_b32_e32 v105, v0
	v_mov_b32_e32 v106, v0
	v_mov_b32_e32 v107, v0
	v_mov_b32_e32 v108, v0
	v_mov_b32_e32 v109, v0
	v_mov_b32_e32 v110, v0
	v_mov_b32_e32 v111, v0
	v_mov_b32_e32 v32, v0
	v_mov_b32_e32 v33, v0
	v_mov_b32_e32 v34, v0
	v_mov_b32_e32 v35, v0
	v_mov_b32_e32 v36, v0
	v_mov_b32_e32 v37, v0
	v_mov_b32_e32 v38, v0
	v_mov_b32_e32 v39, v0
	v_mov_b32_e32 v40, v0
	v_mov_b32_e32 v41, v0
	v_mov_b32_e32 v42, v0
	v_mov_b32_e32 v43, v0
	v_mov_b32_e32 v44, v0
	v_mov_b32_e32 v45, v0
	v_mov_b32_e32 v46, v0
	v_mov_b32_e32 v47, v0
	v_mov_b32_e32 v48, v0
	v_mov_b32_e32 v49, v0
	v_mov_b32_e32 v50, v0
	v_mov_b32_e32 v51, v0
	v_mov_b32_e32 v52, v0
	v_mov_b32_e32 v53, v0
	v_mov_b32_e32 v54, v0
	v_mov_b32_e32 v55, v0
	v_mov_b32_e32 v56, v0
	v_mov_b32_e32 v57, v0
	v_mov_b32_e32 v58, v0
	v_mov_b32_e32 v59, v0
	v_mov_b32_e32 v60, v0
	v_mov_b32_e32 v61, v0
	v_mov_b32_e32 v62, v0
	v_mov_b32_e32 v63, v0
	v_mov_b32_e32 v112, v0
	v_mov_b32_e32 v113, v0
	v_mov_b32_e32 v114, v0
	v_mov_b32_e32 v115, v0
	v_mov_b32_e32 v116, v0
	v_mov_b32_e32 v117, v0
	v_mov_b32_e32 v118, v0
	v_mov_b32_e32 v119, v0
	v_mov_b32_e32 v120, v0
	v_mov_b32_e32 v121, v0
	v_mov_b32_e32 v122, v0
	v_mov_b32_e32 v123, v0
	v_mov_b32_e32 v124, v0
	v_mov_b32_e32 v125, v0
	v_mov_b32_e32 v126, v0
	v_mov_b32_e32 v127, v0
	v_mov_b32_e32 v128, v0
	v_mov_b32_e32 v129, v0
	v_mov_b32_e32 v130, v0
	v_mov_b32_e32 v131, v0
	v_mov_b32_e32 v132, v0
	v_mov_b32_e32 v133, v0
	v_mov_b32_e32 v134, v0
	v_mov_b32_e32 v135, v0
	v_mov_b32_e32 v136, v0
	v_mov_b32_e32 v137, v0
	v_mov_b32_e32 v138, v0
	v_mov_b32_e32 v139, v0
	v_mov_b32_e32 v152, v0
	v_mov_b32_e32 v153, v0
	v_mov_b32_e32 v154, v0
	v_mov_b32_e32 v155, v0

; #define PG8_STAGE(bufoff, gbase, voff) do { _Pragma("unroll") for (int _i = 0; _i < 2; ++_i) \
;         __builtin_amdgcn_global_load_lds((const unsigned*)((const char*)(gbase) + (voff)[_i]), (PG8_LAS unsigned*)(lds + (bufoff) + ldsw + _i * 8192), 16, 0, 0); } while (0)
; #define PG8_WAIT_V(n) asm volatile("s_waitcnt vmcnt(" #n ")" ::: "memory")
; #define PG8_BAR __builtin_amdgcn_s_barrier()
; template <class Epi>
; DI void gemm_phase(PG8_LAS unsigned char* lds, const Gemm g, const StaticOrder& S, const Epi& E) {
;     ...
;     Unit cur, nxt; int ui = 0;
;     if (!S.next(0, cur)) return;
;     f32x4 acc[2][2][4][2];
; #pragma unroll
;     for (int a = 0; a < 2; ++a)
; #pragma unroll
;         for (int b = 0; b < 2; ++b)
; #pragma unroll
;             for (int m = 0; m < 4; ++m)
; #pragma unroll
;                 for (int n = 0; n < 2; ++n) acc[a][b][m][n] = (f32x4){0.f, 0.f, 0.f, 0.f};
;     bf16x8 At[4][2], B0[2][2], B1[2][2];
;     const char* cA = (const char*)g.A + (size_t)cur.pm * tstepA + (size_t)cur.pn * g.a_pn_off; const char* cB = (const char*)g.Bt + (size_t)cur.pn * tstepB;
;     PG8_STAGE(PG8_SB(0, 0), cB, voffB); PG8_STAGE(PG8_SB(0, 1), cB + hstepB, voffB); PG8_STAGE(PG8_SA(0, 0), cA, voffA); PG8_STAGE(PG8_SA(0, 1), cA + hstepA, voffA);
;     if (wr == 1) PG8_BAR;
;     PG8_WAIT_V(2); PG8_BAR;
;     PG8_STAGE(PG8_SB(1, 0), cB + kstep, voffB); PG8_STAGE(PG8_SA(1, 0), cA + kstep, voffA); PG8_STAGE(PG8_SB(1, 1), cB + hstepB + kstep, voffB);
;     PG8_WAIT_V(6); PG8_BAR;
;     for (;;) {
;         const bool has_next = S.next(ui + 1, nxt);
;         const char* nA = has_next ? (const char*)g.A + (size_t)nxt.pm * tstepA + (size_t)nxt.pn * g.a_pn_off : cA; const char* nB = has_next ? (const char*)g.Bt + (size_t)nxt.pn * tstepB : cB;
.LBB0_1223:
	s_getpc_b64 s[100:101]
	v_lshlrev_b32_e32 v222, 6, v250
	v_min_u32_e32 v222, 0x1fc0, v222
	global_load_dword v253, v222, s[100:101]
	s_add_u32 s55, s22, 0x100
	v_mov_b32_e32 v0, 0
	s_addc_u32 s56, s23, 0
	s_mov_b32 s57, -2
	v_mov_b32_e32 v1, v0
	v_mov_b32_e32 v2, v0
	v_mov_b32_e32 v3, v0
	v_mov_b32_e32 v4, v0
	v_mov_b32_e32 v5, v0
	v_mov_b32_e32 v6, v0
	v_mov_b32_e32 v7, v0
	v_mov_b32_e32 v16, v0
	v_mov_b32_e32 v17, v0
	v_mov_b32_e32 v18, v0
	v_mov_b32_e32 v19, v0
	v_mov_b32_e32 v20, v0
	v_mov_b32_e32 v21, v0
	v_mov_b32_e32 v22, v0
	v_mov_b32_e32 v23, v0
	v_mov_b32_e32 v28, v0
	v_mov_b32_e32 v29, v0
	v_mov_b32_e32 v30, v0
	v_mov_b32_e32 v31, v0
	v_mov_b32_e32 v36, v0
	v_mov_b32_e32 v37, v0
	v_mov_b32_e32 v38, v0
	v_mov_b32_e32 v39, v0
	v_mov_b32_e32 v48, v0
	v_mov_b32_e32 v49, v0
	v_mov_b32_e32 v50, v0
	v_mov_b32_e32 v51, v0
	v_mov_b32_e32 v52, v0
	v_mov_b32_e32 v53, v0
	v_mov_b32_e32 v54, v0
	v_mov_b32_e32 v55, v0
	v_mov_b32_e32 v8, v0
	v_mov_b32_e32 v9, v0
	v_mov_b32_e32 v10, v0
	v_mov_b32_e32 v11, v0
	v_mov_b32_e32 v12, v0
	v_mov_b32_e32 v13, v0
	v_mov_b32_e32 v14, v0
	v_mov_b32_e32 v15, v0
	v_mov_b32_e32 v24, v0
	v_mov_b32_e32 v25, v0
	v_mov_b32_e32 v26, v0
	v_mov_b32_e32 v27, v0
	v_mov_b32_e32 v32, v0
	v_mov_b32_e32 v33, v0
	v_mov_b32_e32 v34, v0
	v_mov_b32_e32 v35, v0
	v_mov_b32_e32 v40, v0
	v_mov_b32_e32 v41, v0
	v_mov_b32_e32 v42, v0
	v_mov_b32_e32 v43, v0
	v_mov_b32_e32 v44, v0
	v_mov_b32_e32 v45, v0
	v_mov_b32_e32 v46, v0
	v_mov_b32_e32 v47, v0
	v_mov_b32_e32 v56, v0
	v_mov_b32_e32 v57, v0
	v_mov_b32_e32 v58, v0
	v_mov_b32_e32 v59, v0
	v_mov_b32_e32 v60, v0
	v_mov_b32_e32 v61, v0
	v_mov_b32_e32 v62, v0
	v_mov_b32_e32 v63, v0
	v_mov_b32_e32 v64, v0
	v_mov_b32_e32 v65, v0
	v_mov_b32_e32 v66, v0
	v_mov_b32_e32 v67, v0
	v_mov_b32_e32 v68, v0
	v_mov_b32_e32 v69, v0
	v_mov_b32_e32 v70, v0
	v_mov_b32_e32 v71, v0
	v_mov_b32_e32 v80, v0
	v_mov_b32_e32 v81, v0
	v_mov_b32_e32 v82, v0
	v_mov_b32_e32 v83, v0
	v_mov_b32_e32 v84, v0
	v_mov_b32_e32 v85, v0
	v_mov_b32_e32 v86, v0
	v_mov_b32_e32 v87, v0
	v_mov_b32_e32 v96, v0
	v_mov_b32_e32 v97, v0
	v_mov_b32_e32 v98, v0
	v_mov_b32_e32 v99, v0
	v_mov_b32_e32 v100, v0
	v_mov_b32_e32 v101, v0
	v_mov_b32_e32 v102, v0
	v_mov_b32_e32 v103, v0
	v_mov_b32_e32 v112, v0
	v_mov_b32_e32 v113, v0
	v_mov_b32_e32 v114, v0
	v_mov_b32_e32 v115, v0
	v_mov_b32_e32 v116, v0
	v_mov_b32_e32 v117, v0
	v_mov_b32_e32 v118, v0
	v_mov_b32_e32 v119, v0
	v_mov_b32_e32 v72, v0
	v_mov_b32_e32 v73, v0
	v_mov_b32_e32 v74, v0
	v_mov_b32_e32 v75, v0
	v_mov_b32_e32 v76, v0
	v_mov_b32_e32 v77, v0
	v_mov_b32_e32 v78, v0
	v_mov_b32_e32 v79, v0
	v_mov_b32_e32 v88, v0
	v_mov_b32_e32 v89, v0
	v_mov_b32_e32 v90, v0
	v_mov_b32_e32 v91, v0
	v_mov_b32_e32 v92, v0
	v_mov_b32_e32 v93, v0
	v_mov_b32_e32 v94, v0
	v_mov_b32_e32 v95, v0
	v_mov_b32_e32 v104, v0
	v_mov_b32_e32 v105, v0
	v_mov_b32_e32 v106, v0
	v_mov_b32_e32 v107, v0
	v_mov_b32_e32 v108, v0
	v_mov_b32_e32 v109, v0
	v_mov_b32_e32 v110, v0
	v_mov_b32_e32 v111, v0
	v_mov_b32_e32 v120, v0
	v_mov_b32_e32 v121, v0
	v_mov_b32_e32 v122, v0
	v_mov_b32_e32 v123, v0
	v_mov_b32_e32 v124, v0
	v_mov_b32_e32 v125, v0
	v_mov_b32_e32 v126, v0
	v_mov_b32_e32 v127, v0
